# ml_conv row loop: L2 look-ahead dummy loads three rows ahead (clamped to the run), latch wait vmcnt(3)
# speedup vs baseline: 1.0025x; 1.0025x over previous
.LBB0_596:
	s_or_b64 exec, exec, s[4:5]
	s_waitcnt vmcnt(0)
	v_lshlrev_b32_e32 v192, 16, v174
	v_and_b32_e32 v194, 0xffff0000, v174
	v_lshlrev_b32_e32 v196, 16, v175
	v_and_b32_e32 v198, 0xffff0000, v175
	v_lshlrev_b32_e32 v200, 16, v176
	v_and_b32_e32 v202, 0xffff0000, v176
	v_lshlrev_b32_e32 v204, 16, v177
	v_and_b32_e32 v206, 0xffff0000, v177
	v_lshlrev_b32_e32 v193, 16, v236
	v_and_b32_e32 v195, 0xffff0000, v236
	v_lshlrev_b32_e32 v197, 16, v237
	v_and_b32_e32 v199, 0xffff0000, v237
	v_lshlrev_b32_e32 v201, 16, v238
	v_and_b32_e32 v203, 0xffff0000, v238
	v_lshlrev_b32_e32 v205, 16, v239
	v_and_b32_e32 v207, 0xffff0000, v239
	v_lshlrev_b32_e32 v208, 16, v246
	v_and_b32_e32 v210, 0xffff0000, v246
	v_lshlrev_b32_e32 v212, 16, v247
	v_and_b32_e32 v214, 0xffff0000, v247
	v_lshlrev_b32_e32 v216, 16, v248
	v_and_b32_e32 v218, 0xffff0000, v248
	v_lshlrev_b32_e32 v220, 16, v249
	v_and_b32_e32 v222, 0xffff0000, v249
	s_cmp_lt_i32 s12, 1
	s_cbranch_scc1 .LBB0_605
	v_lshlrev_b64 v[174:175], 13, v[190:191]
	v_mov_b32_e32 v171, v0
	v_lshl_add_u64 v[174:175], s[8:9], 0, v[174:175]
	v_lshl_add_u64 v[174:175], v[174:175], 0, v[170:171]
	global_load_dwordx4 v[174:177], v[174:175], off
	v_and_b32_e32 v1, 32, v172
	v_cmp_eq_u32_e32 vcc, 0, v1
	v_and_b32_e32 v1, 16, v172
	v_cmp_eq_u32_e64 s[4:5], 0, v1
	v_and_b32_e32 v1, 8, v172
	v_lshl_add_u64 v[224:225], s[8:9], 0, v[170:171]
	v_add_u32_e32 v237, s12, v190
	v_add_u32_e32 v237, -1, v237
	v_add_u32_e32 v232, 1, v190
	v_min_i32_e32 v232, v232, v237
	v_ashrrev_i32_e32 v233, 31, v232
	v_lshlrev_b64 v[232:233], 13, v[232:233]
	v_lshl_add_u64 v[232:233], v[224:225], 0, v[232:233]
	global_load_dword v236, v[232:233], off
	v_add_u32_e32 v232, 2, v190
	v_min_i32_e32 v232, v232, v237
	v_ashrrev_i32_e32 v233, 31, v232
	v_lshlrev_b64 v[232:233], 13, v[232:233]
	v_lshl_add_u64 v[232:233], v[224:225], 0, v[232:233]
	global_load_dword v236, v[232:233], off
	v_cmp_lt_i32_e64 s[8:9], v241, v235
	v_cmp_eq_u32_e64 s[6:7], 0, v1
	s_waitcnt vmcnt(39)
	v_mov_b32_e32 v170, v15
	v_cndmask_b32_e64 v1, v234, v241, s[8:9]
	v_cmp_lt_i32_e64 s[8:9], v240, v235
	v_mov_b32_e32 v173, v7
	s_waitcnt vmcnt(34)
	v_mov_b32_e32 v7, v35
	v_cndmask_b32_e64 v15, v234, v240, s[8:9]
	v_lshlrev_b32_e32 v247, 2, v15
	v_xor_b32_e32 v15, 8, v234
	v_cmp_lt_i32_e64 s[8:9], v15, v235
	v_mov_b32_e32 v171, v17
	v_mov_b32_e32 v186, v9
	v_cndmask_b32_e64 v15, v234, v15, s[8:9]
	v_lshlrev_b32_e32 v248, 2, v15
	v_xor_b32_e32 v15, 4, v234
	v_cmp_lt_i32_e64 s[8:9], v15, v235
	v_mov_b32_e32 v9, v37
	v_mov_b32_e32 v35, v26
	v_cndmask_b32_e64 v15, v234, v15, s[8:9]
	v_lshlrev_b32_e32 v249, 2, v15
	v_xor_b32_e32 v15, 2, v234
	v_cmp_lt_i32_e64 s[8:9], v15, v235
	v_mov_b32_e32 v26, v7
	v_mov_b32_e32 v7, v22
	v_cndmask_b32_e64 v15, v234, v15, s[8:9]
	v_lshlrev_b32_e32 v250, 2, v15
	v_xor_b32_e32 v15, 1, v234
	v_cmp_lt_i32_e64 s[8:9], v15, v235
	v_mov_b32_e32 v22, v173
	v_lshrrev_b32_e32 v173, 1, v172
	v_cndmask_b32_e64 v15, v234, v15, s[8:9]
	v_lshlrev_b32_e32 v251, 2, v15
	v_and_b32_e32 v15, 7, v172
	v_cmp_eq_u32_e64 s[8:9], 0, v15
	v_mov_b32_e32 v15, v18
	v_mov_b32_e32 v18, v170
	v_mov_b32_e32 v17, v20
	v_mov_b32_e32 v37, v28
	v_mov_b32_e32 v20, v171
	v_mov_b32_e32 v28, v9
	v_mov_b32_e32 v9, v24
	v_mov_b32_e32 v24, v186
	v_lshlrev_b64 v[170:171], 7, v[190:191]
	v_and_b32_e32 v186, 0x60, v173
	v_and_b32_e32 v173, 28, v173
	v_or3_b32 v170, v170, v186, v173
	v_lshl_add_u64 v[170:171], s[2:3], 0, v[170:171]
	s_mov_b64 s[10:11], 0x1c200000
	v_lshl_add_u64 v[226:227], v[170:171], 0, s[10:11]
	v_lshlrev_b64 v[170:171], 12, v[190:191]
	v_and_b32_e32 v172, 0xff, v172
	v_lshl_or_b32 v170, v172, 4, v170
	s_waitcnt vmcnt(33)
	v_mov_b32_e32 v187, v39
	v_mov_b32_e32 v188, v41
	v_lshl_add_u64 v[170:171], s[2:3], 0, v[170:171]
	s_mov_b64 s[2:3], 0x13200000
	s_mov_b32 s13, 0
	v_lshlrev_b32_e32 v1, 2, v1
	v_mov_b32_e32 v39, v30
	v_mov_b32_e32 v30, v187
	v_mov_b32_e32 v41, v32
	v_mov_b32_e32 v32, v188
	v_lshl_add_u64 v[228:229], v[170:171], 0, s[2:3]
	s_waitcnt vmcnt(0)
	s_branch .LBB0_599
.LBB0_598:
	s_or_b64 exec, exec, s[2:3]
	s_mov_b64 s[2:3], 0x1000
	s_waitcnt vmcnt(3) lgkmcnt(0)
	v_mov_b64_e32 v[176:177], v[172:173]
	v_lshl_add_u64 v[226:227], v[226:227], 0, s[0:1]
	v_lshl_add_u64 v[228:229], v[228:229], 0, s[2:3]
	s_cmp_lg_u32 s12, s13
	v_mov_b32_e32 v192, v193
	v_mov_b32_e32 v194, v195
	v_mov_b32_e32 v196, v197
	v_mov_b32_e32 v198, v199
	v_mov_b32_e32 v200, v201
	v_mov_b32_e32 v202, v203
	v_mov_b32_e32 v204, v205
	v_mov_b32_e32 v206, v207
	v_mov_b64_e32 v[174:175], v[170:171]
	v_mov_b32_e32 v193, v209
	v_mov_b32_e32 v195, v211
	v_mov_b32_e32 v197, v213
	v_mov_b32_e32 v199, v215
	v_mov_b32_e32 v201, v217
	v_mov_b32_e32 v203, v219
	v_mov_b32_e32 v205, v221
	v_mov_b32_e32 v207, v223
	s_cbranch_scc0 .LBB0_605

.LBB0_601:
	s_or_b64 exec, exec, s[2:3]
	s_add_i32 s13, s13, 1
	s_nop 0
	v_mov_b64_e32 v[170:171], v[174:175]
	s_cmp_ge_i32 s13, s12
	v_mov_b64_e32 v[172:173], v[176:177]
	s_cbranch_scc1 .LBB0_603
	v_add_u32_e32 v170, 1, v191
	v_ashrrev_i32_e32 v171, 31, v170
	v_lshlrev_b64 v[170:171], 13, v[170:171]
	v_lshl_add_u64 v[170:171], v[224:225], 0, v[170:171]
	global_load_dwordx4 v[170:173], v[170:171], off
	v_add_u32_e32 v232, 3, v191
	v_min_i32_e32 v232, v232, v237
	v_ashrrev_i32_e32 v233, 31, v232
	v_lshlrev_b64 v[232:233], 13, v[232:233]
	v_lshl_add_u64 v[232:233], v[224:225], 0, v[232:233]
	global_load_dword v236, v[232:233], off
